# RES epilogue: xor-16/xor-32 row-sum butterflies via v_permlane16_swap/v_permlane32_swap instead of ds_bpermute round trips
# baseline (speedup 1.0000x reference)
.LBB0_1353:
	v_pk_mul_f32 v[130:131], v[130:131], v[130:131]
	v_pk_mul_f32 v[132:133], v[132:133], v[132:133]
	v_add_f32_e32 v130, v130, v131
	v_add_f32_e32 v130, v132, v130
	v_pk_mul_f32 v[126:127], v[126:127], v[126:127]
	v_add_f32_e32 v130, v133, v130
	v_add_f32_e32 v126, v126, v130
	v_pk_mul_f32 v[128:129], v[128:129], v[128:129]
	v_add_f32_e32 v126, v127, v126
	v_add_f32_e32 v126, v128, v126
	v_pk_mul_f32 v[118:119], v[118:119], v[118:119]
	v_add_f32_e32 v126, v129, v126
	v_add_f32_e32 v118, v118, v126
	v_pk_mul_f32 v[120:121], v[120:121], v[120:121]
	v_add_f32_e32 v118, v119, v118
	v_add_f32_e32 v118, v120, v118
	v_pk_mul_f32 v[114:115], v[114:115], v[114:115]
	v_add_f32_e32 v118, v121, v118
	v_add_f32_e32 v114, v114, v118
	v_pk_mul_f32 v[116:117], v[116:117], v[116:117]
	v_add_f32_e32 v114, v115, v114
	v_add_f32_e32 v114, v116, v114
	v_and_b32_e32 v116, 64, v211
	v_xor_b32_e32 v115, 16, v211
	v_add_u32_e32 v116, 64, v116
	v_cmp_lt_i32_e32 vcc, v115, v116
	v_add_f32_e32 v114, v117, v114
	v_xor_b32_e32 v117, 32, v211
	v_cndmask_b32_e32 v115, v211, v115, vcc
	v_lshlrev_b32_e32 v120, 2, v115
	v_mov_b32_e32 v115, v114
	s_nop 1
	v_permlane16_swap_b32_e32 v114, v115
	v_cmp_lt_i32_e32 vcc, v117, v116
	s_lshl_b32 s24, s45, 2
	s_ashr_i32 s25, s24, 31
	v_cndmask_b32_e32 v116, v211, v117, vcc
	v_lshlrev_b32_e32 v121, 2, v116
	s_waitcnt lgkmcnt(0)
	v_add_f32_e32 v114, v114, v115
	v_mov_b32_e32 v115, v114
	s_nop 1
	v_permlane32_swap_b32_e32 v114, v115
	s_and_saveexec_b64 s[26:27], s[0:1]
	s_cbranch_execz .LBB0_1355
	v_readlane_b32 s46, v254, 30
	v_lshlrev_b64 v[116:117], 6, v[182:183]
	v_readlane_b32 s47, v254, 31
	s_lshl_b32 s92, s39, 2
	s_waitcnt lgkmcnt(0)
	v_add_f32_e32 v114, v114, v115
	v_lshl_add_u64 v[116:117], s[46:47], 0, v[116:117]
	v_lshl_add_u64 v[116:117], s[24:25], 2, v[116:117]
	v_lshl_add_u64 v[116:117], v[116:117], 0, s[92:93]
	global_store_dword v[116:117], v114, off

.LBB0_1361:
	v_pk_mul_f32 v[110:111], v[110:111], v[110:111]
	v_pk_mul_f32 v[112:113], v[112:113], v[112:113]
	v_add_f32_e32 v110, v110, v111
	v_add_f32_e32 v110, v112, v110
	v_pk_mul_f32 v[106:107], v[106:107], v[106:107]
	v_add_f32_e32 v110, v113, v110
	v_add_f32_e32 v106, v106, v110
	v_pk_mul_f32 v[108:109], v[108:109], v[108:109]
	v_add_f32_e32 v106, v107, v106
	v_add_f32_e32 v106, v108, v106
	v_pk_mul_f32 v[102:103], v[102:103], v[102:103]
	v_add_f32_e32 v106, v109, v106
	v_add_f32_e32 v102, v102, v106
	v_pk_mul_f32 v[104:105], v[104:105], v[104:105]
	v_add_f32_e32 v102, v103, v102
	v_add_f32_e32 v102, v104, v102
	v_pk_mul_f32 v[98:99], v[98:99], v[98:99]
	v_add_f32_e32 v102, v105, v102
	v_add_f32_e32 v98, v98, v102
	v_pk_mul_f32 v[100:101], v[100:101], v[100:101]
	v_add_f32_e32 v98, v99, v98
	v_add_f32_e32 v98, v100, v98
	v_add_f32_e32 v98, v101, v98
	v_mov_b32_e32 v99, v98
	s_nop 1
	v_permlane16_swap_b32_e32 v98, v99
	s_waitcnt lgkmcnt(0)
	v_add_f32_e32 v98, v98, v99
	v_mov_b32_e32 v99, v98
	s_nop 1
	v_permlane32_swap_b32_e32 v98, v99
	s_and_saveexec_b64 s[26:27], s[0:1]
	s_cbranch_execz .LBB0_1363
	v_readlane_b32 s46, v254, 30
	v_lshlrev_b64 v[100:101], 6, v[188:189]
	v_readlane_b32 s47, v254, 31
	s_lshl_b32 s92, s39, 2
	s_waitcnt lgkmcnt(0)
	v_add_f32_e32 v98, v98, v99
	v_lshl_add_u64 v[100:101], s[46:47], 0, v[100:101]
	v_lshl_add_u64 v[100:101], s[24:25], 2, v[100:101]
	v_lshl_add_u64 v[100:101], v[100:101], 0, s[92:93]
	global_store_dword v[100:101], v98, off

.LBB0_1369:
	v_pk_mul_f32 v[94:95], v[94:95], v[94:95]
	v_pk_mul_f32 v[96:97], v[96:97], v[96:97]
	v_add_f32_e32 v94, v94, v95
	v_add_f32_e32 v94, v96, v94
	v_pk_mul_f32 v[90:91], v[90:91], v[90:91]
	v_add_f32_e32 v94, v97, v94
	v_add_f32_e32 v90, v90, v94
	v_pk_mul_f32 v[92:93], v[92:93], v[92:93]
	v_add_f32_e32 v90, v91, v90
	v_add_f32_e32 v90, v92, v90
	v_pk_mul_f32 v[86:87], v[86:87], v[86:87]
	v_add_f32_e32 v90, v93, v90
	v_add_f32_e32 v86, v86, v90
	v_pk_mul_f32 v[88:89], v[88:89], v[88:89]
	v_add_f32_e32 v86, v87, v86
	v_add_f32_e32 v86, v88, v86
	v_pk_mul_f32 v[82:83], v[82:83], v[82:83]
	v_add_f32_e32 v86, v89, v86
	v_add_f32_e32 v82, v82, v86
	v_pk_mul_f32 v[84:85], v[84:85], v[84:85]
	v_add_f32_e32 v82, v83, v82
	v_add_f32_e32 v82, v84, v82
	v_add_f32_e32 v82, v85, v82
	v_mov_b32_e32 v83, v82
	s_nop 1
	v_permlane16_swap_b32_e32 v82, v83
	s_waitcnt lgkmcnt(0)
	v_add_f32_e32 v82, v82, v83
	v_mov_b32_e32 v83, v82
	s_nop 1
	v_permlane32_swap_b32_e32 v82, v83
	s_and_saveexec_b64 s[26:27], s[0:1]
	s_cbranch_execz .LBB0_1371
	v_readlane_b32 s46, v254, 30
	v_lshlrev_b64 v[84:85], 6, v[186:187]
	v_readlane_b32 s47, v254, 31
	s_lshl_b32 s92, s39, 2
	s_waitcnt lgkmcnt(0)
	v_add_f32_e32 v82, v82, v83
	v_lshl_add_u64 v[84:85], s[46:47], 0, v[84:85]
	v_lshl_add_u64 v[84:85], s[24:25], 2, v[84:85]
	v_lshl_add_u64 v[84:85], v[84:85], 0, s[92:93]
	global_store_dword v[84:85], v82, off

.LBB0_1377:
	v_pk_mul_f32 v[78:79], v[78:79], v[78:79]
	v_pk_mul_f32 v[80:81], v[80:81], v[80:81]
	v_add_f32_e32 v78, v78, v79
	v_add_f32_e32 v78, v80, v78
	v_pk_mul_f32 v[74:75], v[74:75], v[74:75]
	v_add_f32_e32 v78, v81, v78
	v_add_f32_e32 v74, v74, v78
	v_pk_mul_f32 v[76:77], v[76:77], v[76:77]
	v_add_f32_e32 v74, v75, v74
	v_add_f32_e32 v74, v76, v74
	v_pk_mul_f32 v[70:71], v[70:71], v[70:71]
	v_add_f32_e32 v74, v77, v74
	v_add_f32_e32 v70, v70, v74
	v_pk_mul_f32 v[72:73], v[72:73], v[72:73]
	v_add_f32_e32 v70, v71, v70
	v_add_f32_e32 v70, v72, v70
	v_pk_mul_f32 v[66:67], v[66:67], v[66:67]
	v_add_f32_e32 v70, v73, v70
	v_add_f32_e32 v66, v66, v70
	v_pk_mul_f32 v[68:69], v[68:69], v[68:69]
	v_add_f32_e32 v66, v67, v66
	v_add_f32_e32 v66, v68, v66
	v_add_f32_e32 v66, v69, v66
	v_mov_b32_e32 v67, v66
	s_nop 1
	v_permlane16_swap_b32_e32 v66, v67
	s_waitcnt lgkmcnt(0)
	v_add_f32_e32 v66, v66, v67
	v_mov_b32_e32 v67, v66
	s_nop 1
	v_permlane32_swap_b32_e32 v66, v67
	s_and_saveexec_b64 s[26:27], s[0:1]
	s_cbranch_execz .LBB0_1379
	v_readlane_b32 s46, v254, 30
	v_lshlrev_b64 v[68:69], 6, v[184:185]
	v_readlane_b32 s47, v254, 31
	s_lshl_b32 s92, s39, 2
	s_waitcnt lgkmcnt(0)
	v_add_f32_e32 v66, v66, v67
	v_lshl_add_u64 v[68:69], s[46:47], 0, v[68:69]
	v_lshl_add_u64 v[68:69], s[24:25], 2, v[68:69]
	v_lshl_add_u64 v[68:69], v[68:69], 0, s[92:93]
	global_store_dword v[68:69], v66, off

.LBB0_1385:
	v_pk_mul_f32 v[62:63], v[62:63], v[62:63]
	v_pk_mul_f32 v[64:65], v[64:65], v[64:65]
	v_add_f32_e32 v62, v62, v63
	v_add_f32_e32 v62, v64, v62
	v_pk_mul_f32 v[58:59], v[58:59], v[58:59]
	v_add_f32_e32 v62, v65, v62
	v_add_f32_e32 v58, v58, v62
	v_pk_mul_f32 v[60:61], v[60:61], v[60:61]
	v_add_f32_e32 v58, v59, v58
	v_add_f32_e32 v58, v60, v58
	v_pk_mul_f32 v[54:55], v[54:55], v[54:55]
	v_add_f32_e32 v58, v61, v58
	v_add_f32_e32 v54, v54, v58
	v_pk_mul_f32 v[56:57], v[56:57], v[56:57]
	v_add_f32_e32 v54, v55, v54
	v_add_f32_e32 v54, v56, v54
	v_pk_mul_f32 v[50:51], v[50:51], v[50:51]
	v_add_f32_e32 v54, v57, v54
	v_add_f32_e32 v50, v50, v54
	v_pk_mul_f32 v[52:53], v[52:53], v[52:53]
	v_add_f32_e32 v50, v51, v50
	v_add_f32_e32 v50, v52, v50
	v_add_f32_e32 v50, v53, v50
	v_mov_b32_e32 v51, v50
	s_nop 1
	v_permlane16_swap_b32_e32 v50, v51
	s_waitcnt lgkmcnt(0)
	v_add_f32_e32 v50, v50, v51
	v_mov_b32_e32 v51, v50
	s_nop 1
	v_permlane32_swap_b32_e32 v50, v51
	s_and_saveexec_b64 s[26:27], s[0:1]
	s_cbranch_execz .LBB0_1387
	v_readlane_b32 s46, v254, 30
	v_lshlrev_b64 v[52:53], 6, v[100:101]
	v_readlane_b32 s47, v254, 31
	s_lshl_b32 s92, s39, 2
	s_waitcnt lgkmcnt(0)
	v_add_f32_e32 v50, v50, v51
	v_lshl_add_u64 v[52:53], s[46:47], 0, v[52:53]
	v_lshl_add_u64 v[52:53], s[24:25], 2, v[52:53]
	v_lshl_add_u64 v[52:53], v[52:53], 0, s[92:93]
	global_store_dword v[52:53], v50, off

.LBB0_1393:
	v_pk_mul_f32 v[46:47], v[46:47], v[46:47]
	v_pk_mul_f32 v[48:49], v[48:49], v[48:49]
	v_add_f32_e32 v46, v46, v47
	v_add_f32_e32 v46, v48, v46
	v_pk_mul_f32 v[42:43], v[42:43], v[42:43]
	v_add_f32_e32 v46, v49, v46
	v_add_f32_e32 v42, v42, v46
	v_pk_mul_f32 v[44:45], v[44:45], v[44:45]
	v_add_f32_e32 v42, v43, v42
	v_add_f32_e32 v42, v44, v42
	v_pk_mul_f32 v[38:39], v[38:39], v[38:39]
	v_add_f32_e32 v42, v45, v42
	v_add_f32_e32 v38, v38, v42
	v_pk_mul_f32 v[40:41], v[40:41], v[40:41]
	v_add_f32_e32 v38, v39, v38
	v_add_f32_e32 v38, v40, v38
	v_pk_mul_f32 v[34:35], v[34:35], v[34:35]
	v_add_f32_e32 v38, v41, v38
	v_add_f32_e32 v34, v34, v38
	v_pk_mul_f32 v[36:37], v[36:37], v[36:37]
	v_add_f32_e32 v34, v35, v34
	v_add_f32_e32 v34, v36, v34
	v_add_f32_e32 v34, v37, v34
	v_mov_b32_e32 v35, v34
	s_nop 1
	v_permlane16_swap_b32_e32 v34, v35
	s_waitcnt lgkmcnt(0)
	v_add_f32_e32 v34, v34, v35
	v_mov_b32_e32 v35, v34
	s_nop 1
	v_permlane32_swap_b32_e32 v34, v35
	s_and_saveexec_b64 s[26:27], s[0:1]
	s_cbranch_execz .LBB0_1395
	v_readlane_b32 s46, v254, 30
	v_lshlrev_b64 v[36:37], 6, v[98:99]
	v_readlane_b32 s47, v254, 31
	s_lshl_b32 s92, s39, 2
	s_waitcnt lgkmcnt(0)
	v_add_f32_e32 v34, v34, v35
	v_lshl_add_u64 v[36:37], s[46:47], 0, v[36:37]
	v_lshl_add_u64 v[36:37], s[24:25], 2, v[36:37]
	v_lshl_add_u64 v[36:37], v[36:37], 0, s[92:93]
	global_store_dword v[36:37], v34, off

.LBB0_1401:
	v_pk_mul_f32 v[30:31], v[30:31], v[30:31]
	v_pk_mul_f32 v[32:33], v[32:33], v[32:33]
	v_add_f32_e32 v30, v30, v31
	v_add_f32_e32 v30, v32, v30
	v_pk_mul_f32 v[26:27], v[26:27], v[26:27]
	v_add_f32_e32 v30, v33, v30
	v_add_f32_e32 v26, v26, v30
	v_pk_mul_f32 v[28:29], v[28:29], v[28:29]
	v_add_f32_e32 v26, v27, v26
	v_add_f32_e32 v26, v28, v26
	v_pk_mul_f32 v[22:23], v[22:23], v[22:23]
	v_add_f32_e32 v26, v29, v26
	v_add_f32_e32 v22, v22, v26
	v_pk_mul_f32 v[24:25], v[24:25], v[24:25]
	v_add_f32_e32 v22, v23, v22
	v_add_f32_e32 v22, v24, v22
	v_pk_mul_f32 v[18:19], v[18:19], v[18:19]
	v_add_f32_e32 v22, v25, v22
	v_add_f32_e32 v18, v18, v22
	v_pk_mul_f32 v[20:21], v[20:21], v[20:21]
	v_add_f32_e32 v18, v19, v18
	v_add_f32_e32 v18, v20, v18
	v_add_f32_e32 v18, v21, v18
	v_mov_b32_e32 v19, v18
	s_nop 1
	v_permlane16_swap_b32_e32 v18, v19
	s_waitcnt lgkmcnt(0)
	v_add_f32_e32 v18, v18, v19
	v_mov_b32_e32 v19, v18
	s_nop 1
	v_permlane32_swap_b32_e32 v18, v19
	s_and_saveexec_b64 s[26:27], s[0:1]
	s_cbranch_execz .LBB0_1403
	v_readlane_b32 s46, v254, 30
	v_lshlrev_b64 v[20:21], 6, v[96:97]
	v_readlane_b32 s47, v254, 31
	s_lshl_b32 s92, s39, 2
	s_waitcnt lgkmcnt(0)
	v_add_f32_e32 v18, v18, v19
	v_lshl_add_u64 v[20:21], s[46:47], 0, v[20:21]
	v_lshl_add_u64 v[20:21], s[24:25], 2, v[20:21]
	v_lshl_add_u64 v[20:21], v[20:21], 0, s[92:93]
	global_store_dword v[20:21], v18, off

.LBB0_1409:
	v_pk_mul_f32 v[14:15], v[14:15], v[14:15]
	v_pk_mul_f32 v[16:17], v[16:17], v[16:17]
	v_add_f32_e32 v14, v14, v15
	v_add_f32_e32 v14, v16, v14
	v_pk_mul_f32 v[10:11], v[10:11], v[10:11]
	v_add_f32_e32 v14, v17, v14
	v_add_f32_e32 v10, v10, v14
	v_pk_mul_f32 v[12:13], v[12:13], v[12:13]
	v_add_f32_e32 v10, v11, v10
	v_add_f32_e32 v10, v12, v10
	v_pk_mul_f32 v[6:7], v[6:7], v[6:7]
	v_add_f32_e32 v10, v13, v10
	v_add_f32_e32 v6, v6, v10
	v_pk_mul_f32 v[8:9], v[8:9], v[8:9]
	v_add_f32_e32 v6, v7, v6
	v_add_f32_e32 v6, v8, v6
	v_pk_mul_f32 v[2:3], v[2:3], v[2:3]
	v_add_f32_e32 v6, v9, v6
	v_add_f32_e32 v2, v2, v6
	v_pk_mul_f32 v[4:5], v[4:5], v[4:5]
	v_add_f32_e32 v2, v3, v2
	v_add_f32_e32 v2, v4, v2
	v_add_f32_e32 v2, v5, v2
	v_mov_b32_e32 v3, v2
	s_nop 1
	v_permlane16_swap_b32_e32 v2, v3
	s_waitcnt lgkmcnt(0)
	v_add_f32_e32 v2, v2, v3
	v_mov_b32_e32 v3, v2
	s_nop 1
	v_permlane32_swap_b32_e32 v2, v3
	s_and_saveexec_b64 s[6:7], s[0:1]
	s_cbranch_execz .LBB0_1411
	v_readlane_b32 s26, v254, 30
	v_lshlrev_b64 v[4:5], 6, v[94:95]
	v_readlane_b32 s27, v254, 31
	s_lshl_b32 s92, s39, 2
	s_waitcnt lgkmcnt(0)
	v_add_f32_e32 v2, v2, v3
	v_lshl_add_u64 v[4:5], s[26:27], 0, v[4:5]
	v_lshl_add_u64 v[4:5], s[24:25], 2, v[4:5]
	v_lshl_add_u64 v[4:5], v[4:5], 0, s[92:93]
	global_store_dword v[4:5], v2, off
